# prologue x->bf16 rows: two-item waves do two of four row iterations, waves 1024..1311 take the rest
# baseline (speedup 1.0000x reference)
; __device__ __forceinline__ unsigned pk2(float lo, float hi) { return f2bf(lo) | (f2bf(hi) << 16); }
; __device__ __forceinline__ void prologue(const Args& a, LAS unsigned char* lds, int vcu, int G, int wave, int lane) {
;     ...
;     for (int m = gw; m < M; m += 2 * NGW) {
;         const int m2 = m + NGW; const bool has2 = m2 < M;
;         const f32x4* x1 = (const f32x4*)(a.in[0] + (size_t)m * D) + lane; const f32x4* x2 = (const f32x4*)(a.in[0] + (size_t)(has2 ? m2 : m) * D) + lane;
;         f32x4 v1[4], v2[4]; float s1 = 0.f, s2 = 0.f;
; #pragma unroll
;         for (int j = 0; j < 4; ++j) { v1[j] = __builtin_nontemporal_load(x1 + 64 * j); v2[j] = __builtin_nontemporal_load(x2 + 64 * j); }
; #pragma unroll
;         for (int j = 0; j < 4; ++j) { s1 += (v1[j].x * v1[j].x + v1[j].y * v1[j].y) + (v1[j].z * v1[j].z + v1[j].w * v1[j].w); s2 += (v2[j].x * v2[j].x + v2[j].y * v2[j].y) + (v2[j].z * v2[j].z + v2[j].w * v2[j].w);
;             ((v2u*)((bf16*)(ws + WS_HRES) + (size_t)m * D) + lane)[64 * j] = (v2u){pk2(v1[j].x, v1[j].y), pk2(v1[j].z, v1[j].w)};
;             if (has2) ((v2u*)((bf16*)(ws + WS_HRES) + (size_t)m2 * D) + lane)[64 * j] = (v2u){pk2(v2[j].x, v2[j].y), pk2(v2[j].z, v2[j].w)}; }
;         s1 = wave_sum(s1); s2 = wave_sum(s2);
;         if (lane == 0) { ((float*)(ws + WS_ROWSS0))[m] = s1; if (has2) ((float*)(ws + WS_ROWSS0))[m2] = s2; }
;         if (lane == 0) { ((float*)(ws + WS_ROWSS))[m] = 0.f; ((float*)(ws + WS_ROWSS2))[m] = 0.f; if (has2) { ((float*)(ws + WS_ROWSS))[m2] = 0.f; ((float*)(ws + WS_ROWSS2))[m2] = 0.f; } }
;     }
.LBB0_53:
	s_cmpk_gt_i32 s8, 0x3fff
	s_cbranch_scc1 .LBB0_69
	s_mov_b32 s98, 0
	v_lshlrev_b32_e32 v34, 3, v1
	v_mov_b32_e32 v35, 0
	v_lshl_add_u64 v[2:3], s[42:43], 0, v[34:35]
	s_mov_b64 s[2:3], 0xe000000
	v_lshl_add_u64 v[36:37], v[2:3], 0, s[2:3]
	v_mbcnt_lo_u32_b32 v2, -1, 0
	v_mbcnt_hi_u32_b32 v2, -1, v2
	v_and_b32_e32 v3, 64, v2
	v_add_u32_e32 v3, 64, v3
	v_xor_b32_e32 v4, 1, v2
	v_cmp_lt_i32_e32 vcc, v4, v3
	v_lshlrev_b32_e32 v34, 4, v1
	v_lshl_add_u64 v[38:39], s[20:21], 0, v[34:35]
	v_cndmask_b32_e32 v4, v2, v4, vcc
	v_lshlrev_b32_e32 v34, 2, v4
	v_xor_b32_e32 v4, 2, v2
	v_cmp_lt_i32_e32 vcc, v4, v3
	s_add_u32 s26, s42, 0x40000
	s_addc_u32 s27, s43, 0
	v_cndmask_b32_e32 v4, v2, v4, vcc
	v_lshlrev_b32_e32 v44, 2, v4
	v_xor_b32_e32 v4, 4, v2
	v_cmp_lt_i32_e32 vcc, v4, v3
	s_add_u32 s44, s42, 0x20000
	s_addc_u32 s45, s43, 0
	v_cndmask_b32_e32 v4, v2, v4, vcc
	v_lshlrev_b32_e32 v45, 2, v4
	v_xor_b32_e32 v4, 8, v2
	v_cmp_lt_i32_e32 vcc, v4, v3
	s_add_u32 s46, s42, 0x30000
	s_addc_u32 s47, s43, 0
	v_cndmask_b32_e32 v4, v2, v4, vcc
	v_lshlrev_b32_e32 v46, 2, v4
	v_xor_b32_e32 v4, 16, v2
	v_cmp_lt_i32_e32 vcc, v4, v3
	s_ashr_i32 s89, s88, 31
	v_cmp_eq_u32_e64 s[6:7], 0, v1
	v_cndmask_b32_e32 v4, v2, v4, vcc
	v_lshlrev_b32_e32 v47, 2, v4
	v_xor_b32_e32 v4, 32, v2
	v_cmp_lt_i32_e32 vcc, v4, v3
	s_movk_i32 s48, 0x7fff
	s_lshl_b64 s[2:3], s[88:89], 2
	v_cndmask_b32_e32 v2, v2, v4, vcc
	v_lshlrev_b32_e32 v48, 2, v2
	v_mov_b32_e32 v49, 1
	s_branch .LBB0_56
.LBB0_55:
	s_or_b64 exec, exec, s[4:5]
	s_add_i32 s8, s10, s52
	s_mov_b32 s88, s52
	s_cmp_eq_u32 s98, 0
	s_cbranch_scc0 .Lmy_xr_chk
	s_and_b32 s99, s8, 0x7ff
	s_cmpk_lt_u32 s99, 0x6e0
	s_cbranch_scc1 .Lmy_xr_light
	s_cmpk_gt_i32 s8, 0x1fff
	s_cbranch_scc1 .LBB0_69
	s_branch .LBB0_56
.Lmy_xr_light:
	s_cmpk_gt_i32 s8, 0x3fff
	s_cbranch_scc0 .LBB0_56
	s_sub_i32 s99, s99, 0x400
	s_cmpk_lt_u32 s99, 0x120
	s_cbranch_scc0 .LBB0_69
	s_mov_b32 s98, 1
	s_add_i32 s8, s99, 0x26e0
	s_branch .LBB0_56
.Lmy_xr_chk:
	s_cmpk_gt_i32 s8, 0x3fff
	s_cbranch_scc1 .LBB0_69
.LBB0_56:
	s_waitcnt lgkmcnt(0)
	s_add_i32 s10, s8, s88
	s_cmpk_gt_i32 s10, 0x3fff
	s_cselect_b64 s[20:21], -1, 0
	s_ashr_i32 s9, s8, 31
	s_lshl_b64 s[4:5], s[8:9], 12
	s_cmpk_lt_i32 s10, 0x4000
	s_cselect_b64 s[22:23], -1, 0
	v_lshl_add_u64 v[2:3], v[38:39], 0, s[4:5]
	s_and_b64 s[4:5], s[22:23], exec
	s_cselect_b32 s4, s10, s8
	s_ashr_i32 s5, s4, 31
	global_load_dwordx4 v[26:29], v[2:3], off nt
	s_lshl_b64 s[4:5], s[4:5], 12
	v_lshl_add_u64 v[6:7], v[38:39], 0, s[4:5]
	global_load_dwordx4 v[18:21], v[2:3], off offset:1024 nt
	global_load_dwordx4 v[10:13], v[2:3], off offset:2048 nt
	s_nop 0
	global_load_dwordx4 v[2:5], v[2:3], off offset:3072 nt
	s_nop 0
	global_load_dwordx4 v[30:33], v[6:7], off nt
	global_load_dwordx4 v[22:25], v[6:7], off offset:1024 nt
	global_load_dwordx4 v[14:17], v[6:7], off offset:2048 nt
	s_nop 0
	global_load_dwordx4 v[6:9], v[6:7], off offset:3072 nt
	s_lshl_b64 s[4:5], s[8:9], 11
	s_ashr_i32 s11, s10, 31
	v_lshl_add_u64 v[42:43], v[36:37], 0, s[4:5]
	s_lshl_b64 s[4:5], s[10:11], 11
	s_mov_b32 s52, s88
	s_and_b64 vcc, exec, s[20:21]
	v_lshl_add_u64 v[40:41], v[36:37], 0, s[4:5]
	s_waitcnt vmcnt(7)
	v_and_b32_sdwa v51, v26, v49 dst_sel:DWORD dst_unused:UNUSED_PAD src0_sel:WORD_1 src1_sel:DWORD
	v_and_b32_sdwa v52, v29, v49 dst_sel:DWORD dst_unused:UNUSED_PAD src0_sel:WORD_1 src1_sel:DWORD
	v_and_b32_sdwa v53, v27, v49 dst_sel:DWORD dst_unused:UNUSED_PAD src0_sel:WORD_1 src1_sel:DWORD
	v_and_b32_sdwa v50, v28, v49 dst_sel:DWORD dst_unused:UNUSED_PAD src0_sel:WORD_1 src1_sel:DWORD
	v_add3_u32 v54, v26, v51, s48
	v_add3_u32 v51, v29, v52, s48
	v_add3_u32 v52, v27, v53, s48
	v_add3_u32 v50, v28, v50, s48
	v_and_b32_e32 v51, 0xffff0000, v51
	v_and_b32_e32 v52, 0xffff0000, v52
	v_or_b32_sdwa v51, v51, v50 dst_sel:DWORD dst_unused:UNUSED_PAD src0_sel:DWORD src1_sel:WORD_1
	v_or_b32_sdwa v50, v52, v54 dst_sel:DWORD dst_unused:UNUSED_PAD src0_sel:DWORD src1_sel:WORD_1
	global_store_dwordx2 v[42:43], v[50:51], off
	s_cbranch_vccnz .LBB0_58
	s_waitcnt vmcnt(4)
	v_and_b32_sdwa v51, v30, v49 dst_sel:DWORD dst_unused:UNUSED_PAD src0_sel:WORD_1 src1_sel:DWORD
	v_add3_u32 v52, v30, v51, s48
	v_and_b32_sdwa v51, v33, v49 dst_sel:DWORD dst_unused:UNUSED_PAD src0_sel:WORD_1 src1_sel:DWORD
	v_and_b32_sdwa v53, v31, v49 dst_sel:DWORD dst_unused:UNUSED_PAD src0_sel:WORD_1 src1_sel:DWORD
	v_and_b32_sdwa v50, v32, v49 dst_sel:DWORD dst_unused:UNUSED_PAD src0_sel:WORD_1 src1_sel:DWORD
	v_add3_u32 v51, v33, v51, s48
	v_add3_u32 v53, v31, v53, s48
	v_add3_u32 v50, v32, v50, s48
	v_and_b32_e32 v51, 0xffff0000, v51
	v_and_b32_e32 v53, 0xffff0000, v53
	v_or_b32_sdwa v51, v51, v50 dst_sel:DWORD dst_unused:UNUSED_PAD src0_sel:DWORD src1_sel:WORD_1
	v_or_b32_sdwa v50, v53, v52 dst_sel:DWORD dst_unused:UNUSED_PAD src0_sel:DWORD src1_sel:WORD_1
	global_store_dwordx2 v[40:41], v[50:51], off
